# in-proj rotary-key block: cos/sin loads as one burst + wide stores, on top of rebalanced tiles and wide epilogue stores
# baseline (speedup 1.0000x reference)
.LBB0_412:
	s_andn2_b64 vcc, exec, s[62:63]
	s_cbranch_vccnz .LBB0_414
	s_waitcnt lgkmcnt(0)
	v_lshlrev_b64 v[66:67], 6, v[136:137]
	v_lshl_add_u64 v[68:69], v[144:145], 0, v[66:67]
	v_lshl_add_u64 v[72:73], v[142:143], 0, v[66:67]
	global_load_dwordx4 v[82:85], v[68:69], off
	global_load_dwordx4 v[86:89], v[72:73], off
	s_mov_b64 s[16:17], 0x400
	v_lshl_add_u64 v[76:77], v[66:67], 0, s[16:17]
	v_lshl_add_u64 v[68:69], v[144:145], 0, v[76:77]
	v_lshl_add_u64 v[72:73], v[142:143], 0, v[76:77]
	global_load_dwordx4 v[90:93], v[68:69], off
	global_load_dwordx4 v[94:97], v[72:73], off
	v_lshl_add_u64 v[76:77], v[66:67], 0, s[36:37]
	v_lshl_add_u64 v[68:69], v[144:145], 0, v[76:77]
	v_lshl_add_u64 v[72:73], v[142:143], 0, v[76:77]
	global_load_dwordx4 v[98:101], v[68:69], off
	global_load_dwordx4 v[102:105], v[72:73], off
	s_mov_b64 s[16:17], 0xc00
	v_lshl_add_u64 v[76:77], v[66:67], 0, s[16:17]
	v_lshl_add_u64 v[68:69], v[144:145], 0, v[76:77]
	v_lshl_add_u64 v[72:73], v[142:143], 0, v[76:77]
	global_load_dwordx4 v[106:109], v[68:69], off
	global_load_dwordx4 v[110:113], v[72:73], off
	v_lshl_add_u64 v[76:77], v[66:67], 0, s[68:69]
	v_lshl_add_u64 v[68:69], v[144:145], 0, v[76:77]
	v_lshl_add_u64 v[72:73], v[142:143], 0, v[76:77]
	global_load_dwordx4 v[114:117], v[68:69], off
	global_load_dwordx4 v[118:121], v[72:73], off
	s_mov_b64 s[16:17], 0x2400
	v_lshl_add_u64 v[76:77], v[66:67], 0, s[16:17]
	v_lshl_add_u64 v[68:69], v[144:145], 0, v[76:77]
	v_lshl_add_u64 v[72:73], v[142:143], 0, v[76:77]
	global_load_dwordx4 v[122:125], v[68:69], off
	global_load_dwordx4 v[126:129], v[72:73], off
	s_mov_b64 s[16:17], 0x2800
	v_lshl_add_u64 v[76:77], v[66:67], 0, s[16:17]
	v_lshl_add_u64 v[68:69], v[144:145], 0, v[76:77]
	v_lshl_add_u64 v[72:73], v[142:143], 0, v[76:77]
	global_load_dwordx4 v[228:231], v[68:69], off
	global_load_dwordx4 v[232:235], v[72:73], off
	s_mov_b64 s[16:17], 0x2c00
	v_lshl_add_u64 v[76:77], v[66:67], 0, s[16:17]
	v_lshl_add_u64 v[68:69], v[144:145], 0, v[76:77]
	v_lshl_add_u64 v[72:73], v[142:143], 0, v[76:77]
	global_load_dwordx4 v[236:239], v[68:69], off
	global_load_dwordx4 v[240:243], v[72:73], off
	s_waitcnt vmcnt(14)
	v_pk_mul_f32 v[76:77], v[60:61], v[88:89]
	v_pk_mul_f32 v[78:79], v[58:59], v[86:87]
	v_pk_mul_f32 v[74:75], v[64:65], v[88:89]
	v_pk_mul_f32 v[72:73], v[62:63], v[86:87]
	v_pk_fma_f32 v[76:77], v[64:65], v[84:85], v[76:77] neg_lo:[0,0,1] neg_hi:[0,0,1]
	v_pk_fma_f32 v[78:79], v[62:63], v[82:83], v[78:79] neg_lo:[0,0,1] neg_hi:[0,0,1]
	v_pk_fma_f32 v[70:71], v[60:61], v[84:85], v[74:75]
	v_pk_fma_f32 v[68:69], v[58:59], v[82:83], v[72:73]
	v_lshl_add_u64 v[72:73], v[140:141], 0, v[66:67]
	v_cvt_pk_bf16_f32 v244, v78, v79
	v_cvt_pk_bf16_f32 v245, v76, v77
	v_cvt_pk_bf16_f32 v246, v68, v69
	v_cvt_pk_bf16_f32 v247, v70, v71
	v_lshl_add_u64 v[72:73], v[72:73], 0, v[226:227]
	v_permlane16_swap_b32_e32 v244, v246
	v_permlane16_swap_b32_e32 v245, v247
	global_store_dwordx4 v[72:73], v[244:247], off
	s_waitcnt vmcnt(13)
	v_pk_mul_f32 v[76:77], v[52:53], v[96:97]
	v_pk_mul_f32 v[78:79], v[50:51], v[94:95]
	v_pk_mul_f32 v[74:75], v[56:57], v[96:97]
	v_pk_mul_f32 v[72:73], v[54:55], v[94:95]
	v_pk_fma_f32 v[76:77], v[56:57], v[92:93], v[76:77] neg_lo:[0,0,1] neg_hi:[0,0,1]
	v_pk_fma_f32 v[78:79], v[54:55], v[90:91], v[78:79] neg_lo:[0,0,1] neg_hi:[0,0,1]
	v_pk_fma_f32 v[70:71], v[52:53], v[92:93], v[74:75]
	v_pk_fma_f32 v[68:69], v[50:51], v[90:91], v[72:73]
	s_mov_b64 s[16:17], 0x400
	v_lshl_add_u64 v[80:81], v[66:67], 0, s[16:17]
	v_lshl_add_u64 v[72:73], v[140:141], 0, v[80:81]
	v_cvt_pk_bf16_f32 v248, v78, v79
	v_cvt_pk_bf16_f32 v249, v76, v77
	v_cvt_pk_bf16_f32 v250, v68, v69
	v_cvt_pk_bf16_f32 v251, v70, v71
	v_lshl_add_u64 v[72:73], v[72:73], 0, v[226:227]
	v_permlane16_swap_b32_e32 v248, v250
	v_permlane16_swap_b32_e32 v249, v251
	global_store_dwordx4 v[72:73], v[248:251], off
	s_waitcnt vmcnt(12)
	v_pk_mul_f32 v[76:77], v[44:45], v[104:105]
	v_pk_mul_f32 v[78:79], v[42:43], v[102:103]
	v_pk_mul_f32 v[74:75], v[48:49], v[104:105]
	v_pk_mul_f32 v[72:73], v[46:47], v[102:103]
	v_pk_fma_f32 v[76:77], v[48:49], v[100:101], v[76:77] neg_lo:[0,0,1] neg_hi:[0,0,1]
	v_pk_fma_f32 v[78:79], v[46:47], v[98:99], v[78:79] neg_lo:[0,0,1] neg_hi:[0,0,1]
	v_pk_fma_f32 v[70:71], v[44:45], v[100:101], v[74:75]
	v_pk_fma_f32 v[68:69], v[42:43], v[98:99], v[72:73]
	v_lshl_add_u64 v[80:81], v[66:67], 0, s[36:37]
	v_lshl_add_u64 v[72:73], v[140:141], 0, v[80:81]
	v_cvt_pk_bf16_f32 v244, v78, v79
	v_cvt_pk_bf16_f32 v245, v76, v77
	v_cvt_pk_bf16_f32 v246, v68, v69
	v_cvt_pk_bf16_f32 v247, v70, v71
	v_lshl_add_u64 v[72:73], v[72:73], 0, v[226:227]
	v_permlane16_swap_b32_e32 v244, v246
	v_permlane16_swap_b32_e32 v245, v247
	global_store_dwordx4 v[72:73], v[244:247], off
	s_waitcnt vmcnt(11)
	v_pk_mul_f32 v[76:77], v[36:37], v[112:113]
	v_pk_mul_f32 v[78:79], v[34:35], v[110:111]
	v_pk_mul_f32 v[74:75], v[40:41], v[112:113]
	v_pk_mul_f32 v[72:73], v[38:39], v[110:111]
	v_pk_fma_f32 v[76:77], v[40:41], v[108:109], v[76:77] neg_lo:[0,0,1] neg_hi:[0,0,1]
	v_pk_fma_f32 v[78:79], v[38:39], v[106:107], v[78:79] neg_lo:[0,0,1] neg_hi:[0,0,1]
	v_pk_fma_f32 v[70:71], v[36:37], v[108:109], v[74:75]
	v_pk_fma_f32 v[68:69], v[34:35], v[106:107], v[72:73]
	s_mov_b64 s[16:17], 0xc00
	v_lshl_add_u64 v[80:81], v[66:67], 0, s[16:17]
	v_lshl_add_u64 v[72:73], v[140:141], 0, v[80:81]
	v_cvt_pk_bf16_f32 v248, v78, v79
	v_cvt_pk_bf16_f32 v249, v76, v77
	v_cvt_pk_bf16_f32 v250, v68, v69
	v_cvt_pk_bf16_f32 v251, v70, v71
	v_lshl_add_u64 v[72:73], v[72:73], 0, v[226:227]
	v_permlane16_swap_b32_e32 v248, v250
	v_permlane16_swap_b32_e32 v249, v251
	global_store_dwordx4 v[72:73], v[248:251], off
	s_waitcnt vmcnt(10)
	v_pk_mul_f32 v[76:77], v[28:29], v[120:121]
	v_pk_mul_f32 v[78:79], v[26:27], v[118:119]
	v_pk_mul_f32 v[74:75], v[32:33], v[120:121]
	v_pk_mul_f32 v[72:73], v[30:31], v[118:119]
	v_pk_fma_f32 v[76:77], v[32:33], v[116:117], v[76:77] neg_lo:[0,0,1] neg_hi:[0,0,1]
	v_pk_fma_f32 v[78:79], v[30:31], v[114:115], v[78:79] neg_lo:[0,0,1] neg_hi:[0,0,1]
	v_pk_fma_f32 v[70:71], v[28:29], v[116:117], v[74:75]
	v_pk_fma_f32 v[68:69], v[26:27], v[114:115], v[72:73]
	v_lshl_add_u64 v[80:81], v[66:67], 0, s[68:69]
	v_lshl_add_u64 v[72:73], v[140:141], 0, v[80:81]
	v_cvt_pk_bf16_f32 v244, v78, v79
	v_cvt_pk_bf16_f32 v245, v76, v77
	v_cvt_pk_bf16_f32 v246, v68, v69
	v_cvt_pk_bf16_f32 v247, v70, v71
	v_lshl_add_u64 v[72:73], v[72:73], 0, v[226:227]
	v_permlane16_swap_b32_e32 v244, v246
	v_permlane16_swap_b32_e32 v245, v247
	global_store_dwordx4 v[72:73], v[244:247], off
	s_waitcnt vmcnt(9)
	v_pk_mul_f32 v[76:77], v[20:21], v[128:129]
	v_pk_mul_f32 v[78:79], v[18:19], v[126:127]
	v_pk_mul_f32 v[74:75], v[24:25], v[128:129]
	v_pk_mul_f32 v[72:73], v[22:23], v[126:127]
	v_pk_fma_f32 v[76:77], v[24:25], v[124:125], v[76:77] neg_lo:[0,0,1] neg_hi:[0,0,1]
	v_pk_fma_f32 v[78:79], v[22:23], v[122:123], v[78:79] neg_lo:[0,0,1] neg_hi:[0,0,1]
	v_pk_fma_f32 v[70:71], v[20:21], v[124:125], v[74:75]
	v_pk_fma_f32 v[68:69], v[18:19], v[122:123], v[72:73]
	s_mov_b64 s[16:17], 0x2400
	v_lshl_add_u64 v[80:81], v[66:67], 0, s[16:17]
	v_lshl_add_u64 v[72:73], v[140:141], 0, v[80:81]
	v_cvt_pk_bf16_f32 v248, v78, v79
	v_cvt_pk_bf16_f32 v249, v76, v77
	v_cvt_pk_bf16_f32 v250, v68, v69
	v_cvt_pk_bf16_f32 v251, v70, v71
	v_lshl_add_u64 v[72:73], v[72:73], 0, v[226:227]
	v_permlane16_swap_b32_e32 v248, v250
	v_permlane16_swap_b32_e32 v249, v251
	global_store_dwordx4 v[72:73], v[248:251], off
	s_waitcnt vmcnt(8)
	v_pk_mul_f32 v[76:77], v[10:11], v[234:235]
	v_pk_mul_f32 v[78:79], v[8:9], v[232:233]
	v_pk_mul_f32 v[74:75], v[16:17], v[234:235]
	v_pk_mul_f32 v[72:73], v[14:15], v[232:233]
	v_pk_fma_f32 v[76:77], v[16:17], v[230:231], v[76:77] neg_lo:[0,0,1] neg_hi:[0,0,1]
	v_pk_fma_f32 v[78:79], v[14:15], v[228:229], v[78:79] neg_lo:[0,0,1] neg_hi:[0,0,1]
	v_pk_fma_f32 v[70:71], v[10:11], v[230:231], v[74:75]
	v_pk_fma_f32 v[68:69], v[8:9], v[228:229], v[72:73]
	s_mov_b64 s[16:17], 0x2800
	v_lshl_add_u64 v[80:81], v[66:67], 0, s[16:17]
	v_lshl_add_u64 v[72:73], v[140:141], 0, v[80:81]
	v_cvt_pk_bf16_f32 v244, v78, v79
	v_cvt_pk_bf16_f32 v245, v76, v77
	v_cvt_pk_bf16_f32 v246, v68, v69
	v_cvt_pk_bf16_f32 v247, v70, v71
	v_lshl_add_u64 v[72:73], v[72:73], 0, v[226:227]
	v_permlane16_swap_b32_e32 v244, v246
	v_permlane16_swap_b32_e32 v245, v247
	global_store_dwordx4 v[72:73], v[244:247], off
	s_waitcnt vmcnt(7)
	v_pk_mul_f32 v[76:77], v[2:3], v[242:243]
	v_pk_mul_f32 v[78:79], v[0:1], v[240:241]
	v_pk_mul_f32 v[74:75], v[6:7], v[242:243]
	v_pk_mul_f32 v[72:73], v[4:5], v[240:241]
	v_pk_fma_f32 v[76:77], v[6:7], v[238:239], v[76:77] neg_lo:[0,0,1] neg_hi:[0,0,1]
	v_pk_fma_f32 v[78:79], v[4:5], v[236:237], v[78:79] neg_lo:[0,0,1] neg_hi:[0,0,1]
	v_pk_fma_f32 v[70:71], v[2:3], v[238:239], v[74:75]
	v_pk_fma_f32 v[68:69], v[0:1], v[236:237], v[72:73]
	s_mov_b64 s[16:17], 0x2c00
	v_lshl_add_u64 v[80:81], v[66:67], 0, s[16:17]
	v_lshl_add_u64 v[72:73], v[140:141], 0, v[80:81]
	v_cvt_pk_bf16_f32 v248, v78, v79
	v_cvt_pk_bf16_f32 v249, v76, v77
	v_cvt_pk_bf16_f32 v250, v68, v69
	v_cvt_pk_bf16_f32 v251, v70, v71
	v_lshl_add_u64 v[72:73], v[72:73], 0, v[226:227]
	v_permlane16_swap_b32_e32 v248, v250
	v_permlane16_swap_b32_e32 v249, v251
	global_store_dwordx4 v[72:73], v[248:251], off

.LBB0_415:
	s_andn2_b64 vcc, exec, s[62:63]
	s_cbranch_vccnz .LBB0_417
	v_add_u32_e32 v66, s53, v139
	s_waitcnt lgkmcnt(0)
	v_ashrrev_i32_e32 v67, 31, v66
	v_lshl_add_u64 v[66:67], v[66:67], 1, s[44:45]
	v_lshlrev_b64 v[68:69], 9, v[136:137]
	v_lshl_add_u64 v[66:67], v[66:67], 0, v[68:69]
	s_movk_i32 s16, 0x2000
	v_cvt_pk_bf16_f32 v244, v62, v63
	v_cvt_pk_bf16_f32 v245, v64, v65
	v_add_co_u32_e32 v72, vcc, s16, v66
	v_cvt_pk_bf16_f32 v246, v58, v59
	v_cvt_pk_bf16_f32 v247, v60, v61
	v_cvt_pk_bf16_f32 v248, v54, v55
	v_cvt_pk_bf16_f32 v249, v56, v57
	v_addc_co_u32_e32 v73, vcc, 0, v67, vcc
	s_nop 1
	v_permlane16_swap_b32_e32 v244, v246
	v_permlane16_swap_b32_e32 v245, v247
	v_lshl_add_u64 v[216:217], v[66:67], 0, v[226:227]
	global_store_dwordx4 v[216:217], v[244:247], off
	v_lshl_add_u64 v[68:69], v[66:67], 0, s[68:69]
	v_cvt_pk_bf16_f32 v250, v50, v51
	v_cvt_pk_bf16_f32 v251, v52, v53
	s_mov_b64 s[16:17], 0x4000
	s_nop 1
	v_permlane16_swap_b32_e32 v248, v250
	v_permlane16_swap_b32_e32 v249, v251
	v_lshl_add_u64 v[218:219], v[68:69], 0, v[226:227]
	global_store_dwordx4 v[218:219], v[248:251], off
	v_lshl_add_u64 v[68:69], v[66:67], 0, s[16:17]
	s_movk_i32 s16, 0x4000
	v_add_co_u32_e32 v72, vcc, s16, v66
	v_cvt_pk_bf16_f32 v228, v46, v47
	v_cvt_pk_bf16_f32 v229, v48, v49
	v_addc_co_u32_e32 v73, vcc, 0, v67, vcc
	v_cvt_pk_bf16_f32 v230, v42, v43
	v_cvt_pk_bf16_f32 v231, v44, v45
	s_mov_b64 s[16:17], 0x6000
	s_nop 1
	v_permlane16_swap_b32_e32 v228, v230
	v_permlane16_swap_b32_e32 v229, v231
	v_lshl_add_u64 v[214:215], v[68:69], 0, v[226:227]
	global_store_dwordx4 v[214:215], v[228:231], off
	v_lshl_add_u64 v[68:69], v[66:67], 0, s[16:17]
	s_movk_i32 s16, 0x6000
	v_add_co_u32_e32 v72, vcc, s16, v66
	v_cvt_pk_bf16_f32 v232, v38, v39
	v_cvt_pk_bf16_f32 v233, v40, v41
	v_addc_co_u32_e32 v73, vcc, 0, v67, vcc
	v_cvt_pk_bf16_f32 v234, v34, v35
	v_cvt_pk_bf16_f32 v235, v36, v37
	s_mov_b64 s[16:17], 0x10000
	s_nop 1
	v_permlane16_swap_b32_e32 v232, v234
	v_permlane16_swap_b32_e32 v233, v235
	v_lshl_add_u64 v[216:217], v[68:69], 0, v[226:227]
	global_store_dwordx4 v[216:217], v[232:235], off
	v_lshl_add_u64 v[68:69], v[66:67], 0, s[16:17]
	s_mov_b32 s16, 0x10000
	v_add_co_u32_e32 v72, vcc, s16, v66
	v_cvt_pk_bf16_f32 v236, v30, v31
	v_cvt_pk_bf16_f32 v237, v32, v33
	v_addc_co_u32_e32 v73, vcc, 0, v67, vcc
	v_cvt_pk_bf16_f32 v238, v26, v27
	v_cvt_pk_bf16_f32 v239, v28, v29
	s_mov_b64 s[16:17], 0x12000
	s_nop 1
	v_permlane16_swap_b32_e32 v236, v238
	v_permlane16_swap_b32_e32 v237, v239
	v_lshl_add_u64 v[218:219], v[68:69], 0, v[226:227]
	global_store_dwordx4 v[218:219], v[236:239], off
	v_lshl_add_u64 v[68:69], v[66:67], 0, s[16:17]
	s_mov_b32 s16, 0x12000
	v_add_co_u32_e32 v72, vcc, s16, v66
	v_cvt_pk_bf16_f32 v240, v22, v23
	v_cvt_pk_bf16_f32 v241, v24, v25
	v_addc_co_u32_e32 v73, vcc, 0, v67, vcc
	v_cvt_pk_bf16_f32 v242, v18, v19
	v_cvt_pk_bf16_f32 v243, v20, v21
	s_mov_b64 s[16:17], 0x14000
	s_nop 1
	v_permlane16_swap_b32_e32 v240, v242
	v_permlane16_swap_b32_e32 v241, v243
	v_lshl_add_u64 v[214:215], v[68:69], 0, v[226:227]
	global_store_dwordx4 v[214:215], v[240:243], off
	v_lshl_add_u64 v[68:69], v[66:67], 0, s[16:17]
	s_mov_b32 s16, 0x14000
	v_add_co_u32_e32 v72, vcc, s16, v66
	v_cvt_pk_bf16_f32 v244, v14, v15
	v_cvt_pk_bf16_f32 v245, v16, v17
	v_addc_co_u32_e32 v73, vcc, 0, v67, vcc
	v_cvt_pk_bf16_f32 v246, v8, v9
	v_cvt_pk_bf16_f32 v247, v10, v11
	s_mov_b64 s[16:17], 0x16000
	s_nop 1
	v_permlane16_swap_b32_e32 v244, v246
	v_permlane16_swap_b32_e32 v245, v247
	v_lshl_add_u64 v[216:217], v[68:69], 0, v[226:227]
	global_store_dwordx4 v[216:217], v[244:247], off
	v_lshl_add_u64 v[68:69], v[66:67], 0, s[16:17]
	v_add_co_u32_e32 v66, vcc, 0x16000, v66
	v_cvt_pk_bf16_f32 v248, v4, v5
	v_cvt_pk_bf16_f32 v249, v6, v7
	v_addc_co_u32_e32 v67, vcc, 0, v67, vcc
	v_cvt_pk_bf16_f32 v250, v0, v1
	v_cvt_pk_bf16_f32 v251, v2, v3
	s_nop 1
	v_permlane16_swap_b32_e32 v248, v250
	v_permlane16_swap_b32_e32 v249, v251
	v_lshl_add_u64 v[218:219], v[68:69], 0, v[226:227]
	global_store_dwordx4 v[218:219], v[248:251], off

.LBB0_418:
	s_andn2_b64 vcc, exec, s[62:63]
	s_cbranch_vccnz .LBB0_420
	s_and_b64 s[16:17], s[60:61], exec
	s_movk_i32 s16, 0xfa00
	s_cselect_b32 s16, s16, 0xfffff860
	s_add_i32 s16, s16, s53
	v_add_u32_e32 v66, s16, v138
	v_readlane_b32 s16, v253, 38
	s_waitcnt lgkmcnt(0)
	v_ashrrev_i32_e32 v67, 31, v66
	v_readlane_b32 s17, v253, 39
	v_lshlrev_b64 v[68:69], 11, v[136:137]
	v_mul_f32_e32 v70, 0xbfb8aa3b, v64
	v_lshl_add_u64 v[66:67], v[66:67], 1, s[16:17]
	v_lshl_add_u64 v[66:67], v[66:67], 0, v[68:69]
	v_mul_f32_e32 v68, 0xbfb8aa3b, v62
	v_mul_f32_e32 v69, 0xbfb8aa3b, v63
	v_mul_f32_e32 v71, 0xbfb8aa3b, v65
	v_exp_f32_e32 v68, v68
	v_exp_f32_e32 v69, v69
	v_exp_f32_e32 v70, v70
	v_exp_f32_e32 v71, v71
	v_add_f32_e32 v68, 1.0, v68
	v_add_f32_e32 v69, 1.0, v69
	v_add_f32_e32 v70, 1.0, v70
	v_add_f32_e32 v71, 1.0, v71
	v_rcp_f32_e32 v68, v68
	v_rcp_f32_e32 v69, v69
	v_rcp_f32_e32 v70, v70
	v_rcp_f32_e32 v71, v71
	v_mul_f32_e32 v72, 0xbfb8aa3b, v56
	v_pk_mul_f32 v[68:69], v[62:63], v[68:69]
	v_mul_f32_e32 v73, 0xbfb8aa3b, v57
	v_pk_mul_f32 v[70:71], v[64:65], v[70:71]
	v_cvt_pk_bf16_f32 v228, v68, v69
	v_cvt_pk_bf16_f32 v229, v70, v71
	v_mul_f32_e32 v68, 0xbfb8aa3b, v58
	v_mul_f32_e32 v69, 0xbfb8aa3b, v59
	v_mul_f32_e32 v70, 0xbfb8aa3b, v60
	v_mul_f32_e32 v71, 0xbfb8aa3b, v61
	v_exp_f32_e32 v68, v68
	v_exp_f32_e32 v69, v69
	v_exp_f32_e32 v70, v70
	v_exp_f32_e32 v71, v71
	v_add_f32_e32 v68, 1.0, v68
	v_add_f32_e32 v69, 1.0, v69
	v_add_f32_e32 v70, 1.0, v70
	v_add_f32_e32 v71, 1.0, v71
	v_rcp_f32_e32 v68, v68
	v_rcp_f32_e32 v69, v69
	v_rcp_f32_e32 v70, v70
	v_rcp_f32_e32 v71, v71
	v_exp_f32_e32 v72, v72
	v_pk_mul_f32 v[68:69], v[58:59], v[68:69]
	v_exp_f32_e32 v73, v73
	v_pk_mul_f32 v[70:71], v[60:61], v[70:71]
	v_cvt_pk_bf16_f32 v230, v68, v69
	v_cvt_pk_bf16_f32 v231, v70, v71
	v_mul_f32_e32 v70, 0xbfb8aa3b, v54
	v_mul_f32_e32 v71, 0xbfb8aa3b, v55
	v_exp_f32_e32 v70, v70
	v_exp_f32_e32 v71, v71
	v_add_f32_e32 v72, 1.0, v72
	v_add_f32_e32 v73, 1.0, v73
	v_add_f32_e32 v70, 1.0, v70
	v_add_f32_e32 v71, 1.0, v71
	v_rcp_f32_e32 v70, v70
	v_rcp_f32_e32 v71, v71
	v_rcp_f32_e32 v72, v72
	v_rcp_f32_e32 v73, v73
	s_mov_b64 s[16:17], 0x8000
	s_nop 1
	v_permlane16_swap_b32_e32 v228, v230
	v_permlane16_swap_b32_e32 v229, v231
	v_lshl_add_u64 v[214:215], v[66:67], 0, v[226:227]
	global_store_dwordx4 v[214:215], v[228:231], off
	v_lshl_add_u64 v[68:69], v[66:67], 0, s[16:17]
	v_pk_mul_f32 v[70:71], v[54:55], v[70:71]
	v_pk_mul_f32 v[72:73], v[56:57], v[72:73]
	s_mov_b32 s16, 0x8000
	v_cvt_pk_bf16_f32 v232, v70, v71
	v_cvt_pk_bf16_f32 v233, v72, v73
	v_add_co_u32_e32 v72, vcc, s16, v66
	s_mov_b64 s[16:17], 0x10000
	s_nop 0
	v_addc_co_u32_e32 v73, vcc, 0, v67, vcc
	v_mul_f32_e32 v70, 0xbfb8aa3b, v50
	v_mul_f32_e32 v71, 0xbfb8aa3b, v51
	v_mul_f32_e32 v72, 0xbfb8aa3b, v52
	v_mul_f32_e32 v73, 0xbfb8aa3b, v53
	v_exp_f32_e32 v70, v70
	v_exp_f32_e32 v71, v71
	v_exp_f32_e32 v72, v72
	v_exp_f32_e32 v73, v73
	v_add_f32_e32 v70, 1.0, v70
	v_add_f32_e32 v71, 1.0, v71
	v_add_f32_e32 v72, 1.0, v72
	v_add_f32_e32 v73, 1.0, v73
	v_rcp_f32_e32 v70, v70
	v_rcp_f32_e32 v71, v71
	v_rcp_f32_e32 v72, v72
	v_rcp_f32_e32 v73, v73
	v_pk_mul_f32 v[70:71], v[50:51], v[70:71]
	s_nop 0
	v_cvt_pk_bf16_f32 v234, v70, v71
	v_pk_mul_f32 v[72:73], v[52:53], v[72:73]
	s_nop 0
	v_cvt_pk_bf16_f32 v235, v72, v73
	s_nop 1
	v_permlane16_swap_b32_e32 v232, v234
	v_permlane16_swap_b32_e32 v233, v235
	v_lshl_add_u64 v[216:217], v[68:69], 0, v[226:227]
	global_store_dwordx4 v[216:217], v[232:235], off
	v_mul_f32_e32 v70, 0xbfb8aa3b, v46
	v_mul_f32_e32 v71, 0xbfb8aa3b, v47
	v_mul_f32_e32 v72, 0xbfb8aa3b, v48
	v_mul_f32_e32 v73, 0xbfb8aa3b, v49
	v_exp_f32_e32 v70, v70
	v_exp_f32_e32 v71, v71
	v_exp_f32_e32 v72, v72
	v_exp_f32_e32 v73, v73
	v_add_f32_e32 v70, 1.0, v70
	v_add_f32_e32 v71, 1.0, v71
	v_add_f32_e32 v72, 1.0, v72
	v_add_f32_e32 v73, 1.0, v73
	v_rcp_f32_e32 v70, v70
	v_rcp_f32_e32 v71, v71
	v_rcp_f32_e32 v72, v72
	v_rcp_f32_e32 v73, v73
	v_lshl_add_u64 v[68:69], v[66:67], 0, s[16:17]
	v_pk_mul_f32 v[70:71], v[46:47], v[70:71]
	s_mov_b32 s16, 0x10000
	v_pk_mul_f32 v[72:73], v[48:49], v[72:73]
	v_cvt_pk_bf16_f32 v236, v70, v71
	v_cvt_pk_bf16_f32 v237, v72, v73
	v_add_co_u32_e32 v72, vcc, s16, v66
	s_mov_b64 s[16:17], 0x18000
	s_nop 0
	v_addc_co_u32_e32 v73, vcc, 0, v67, vcc
	v_mul_f32_e32 v70, 0xbfb8aa3b, v42
	v_mul_f32_e32 v71, 0xbfb8aa3b, v43
	v_mul_f32_e32 v72, 0xbfb8aa3b, v44
	v_mul_f32_e32 v73, 0xbfb8aa3b, v45
	v_exp_f32_e32 v70, v70
	v_exp_f32_e32 v71, v71
	v_exp_f32_e32 v72, v72
	v_exp_f32_e32 v73, v73
	v_add_f32_e32 v70, 1.0, v70
	v_add_f32_e32 v71, 1.0, v71
	v_add_f32_e32 v72, 1.0, v72
	v_add_f32_e32 v73, 1.0, v73
	v_rcp_f32_e32 v70, v70
	v_rcp_f32_e32 v71, v71
	v_rcp_f32_e32 v72, v72
	v_rcp_f32_e32 v73, v73
	v_pk_mul_f32 v[70:71], v[42:43], v[70:71]
	s_nop 0
	v_cvt_pk_bf16_f32 v238, v70, v71
	v_pk_mul_f32 v[72:73], v[44:45], v[72:73]
	s_nop 0
	v_cvt_pk_bf16_f32 v239, v72, v73
	s_nop 1
	v_permlane16_swap_b32_e32 v236, v238
	v_permlane16_swap_b32_e32 v237, v239
	v_lshl_add_u64 v[218:219], v[68:69], 0, v[226:227]
	global_store_dwordx4 v[218:219], v[236:239], off
	v_mul_f32_e32 v70, 0xbfb8aa3b, v38
	v_mul_f32_e32 v71, 0xbfb8aa3b, v39
	v_mul_f32_e32 v72, 0xbfb8aa3b, v40
	v_mul_f32_e32 v73, 0xbfb8aa3b, v41
	v_exp_f32_e32 v70, v70
	v_exp_f32_e32 v71, v71
	v_exp_f32_e32 v72, v72
	v_exp_f32_e32 v73, v73
	v_add_f32_e32 v70, 1.0, v70
	v_add_f32_e32 v71, 1.0, v71
	v_add_f32_e32 v72, 1.0, v72
	v_add_f32_e32 v73, 1.0, v73
	v_rcp_f32_e32 v70, v70
	v_rcp_f32_e32 v71, v71
	v_rcp_f32_e32 v72, v72
	v_rcp_f32_e32 v73, v73
	v_lshl_add_u64 v[68:69], v[66:67], 0, s[16:17]
	v_pk_mul_f32 v[70:71], v[38:39], v[70:71]
	s_mov_b32 s16, 0x18000
	v_pk_mul_f32 v[72:73], v[40:41], v[72:73]
	v_cvt_pk_bf16_f32 v240, v70, v71
	v_cvt_pk_bf16_f32 v241, v72, v73
	v_add_co_u32_e32 v72, vcc, s16, v66
	s_mov_b64 s[16:17], 0x40000
	s_nop 0
	v_addc_co_u32_e32 v73, vcc, 0, v67, vcc
	v_mul_f32_e32 v70, 0xbfb8aa3b, v34
	v_mul_f32_e32 v71, 0xbfb8aa3b, v35
	v_mul_f32_e32 v72, 0xbfb8aa3b, v36
	v_mul_f32_e32 v73, 0xbfb8aa3b, v37
	v_exp_f32_e32 v70, v70
	v_exp_f32_e32 v71, v71
	v_exp_f32_e32 v72, v72
	v_exp_f32_e32 v73, v73
	v_add_f32_e32 v70, 1.0, v70
	v_add_f32_e32 v71, 1.0, v71
	v_add_f32_e32 v72, 1.0, v72
	v_add_f32_e32 v73, 1.0, v73
	v_rcp_f32_e32 v70, v70
	v_rcp_f32_e32 v71, v71
	v_rcp_f32_e32 v72, v72
	v_rcp_f32_e32 v73, v73
	v_pk_mul_f32 v[70:71], v[34:35], v[70:71]
	s_nop 0
	v_cvt_pk_bf16_f32 v242, v70, v71
	v_pk_mul_f32 v[72:73], v[36:37], v[72:73]
	s_nop 0
	v_cvt_pk_bf16_f32 v243, v72, v73
	s_nop 1
	v_permlane16_swap_b32_e32 v240, v242
	v_permlane16_swap_b32_e32 v241, v243
	v_lshl_add_u64 v[214:215], v[68:69], 0, v[226:227]
	global_store_dwordx4 v[214:215], v[240:243], off
	v_mul_f32_e32 v70, 0xbfb8aa3b, v30
	v_mul_f32_e32 v71, 0xbfb8aa3b, v31
	v_mul_f32_e32 v72, 0xbfb8aa3b, v32
	v_mul_f32_e32 v73, 0xbfb8aa3b, v33
	v_exp_f32_e32 v70, v70
	v_exp_f32_e32 v71, v71
	v_exp_f32_e32 v72, v72
	v_exp_f32_e32 v73, v73
	v_add_f32_e32 v70, 1.0, v70
	v_add_f32_e32 v71, 1.0, v71
	v_add_f32_e32 v72, 1.0, v72
	v_add_f32_e32 v73, 1.0, v73
	v_rcp_f32_e32 v70, v70
	v_rcp_f32_e32 v71, v71
	v_rcp_f32_e32 v72, v72
	v_rcp_f32_e32 v73, v73
	v_lshl_add_u64 v[68:69], v[66:67], 0, s[16:17]
	v_pk_mul_f32 v[70:71], v[30:31], v[70:71]
	s_mov_b32 s16, 0x40000
	v_pk_mul_f32 v[72:73], v[32:33], v[72:73]
	v_cvt_pk_bf16_f32 v244, v70, v71
	v_cvt_pk_bf16_f32 v245, v72, v73
	v_add_co_u32_e32 v72, vcc, s16, v66
	s_mov_b64 s[16:17], 0x48000
	s_nop 0
	v_addc_co_u32_e32 v73, vcc, 0, v67, vcc
	v_mul_f32_e32 v70, 0xbfb8aa3b, v26
	v_mul_f32_e32 v71, 0xbfb8aa3b, v27
	v_mul_f32_e32 v72, 0xbfb8aa3b, v28
	v_mul_f32_e32 v73, 0xbfb8aa3b, v29
	v_exp_f32_e32 v70, v70
	v_exp_f32_e32 v71, v71
	v_exp_f32_e32 v72, v72
	v_exp_f32_e32 v73, v73
	v_add_f32_e32 v70, 1.0, v70
	v_add_f32_e32 v71, 1.0, v71
	v_add_f32_e32 v72, 1.0, v72
	v_add_f32_e32 v73, 1.0, v73
	v_rcp_f32_e32 v70, v70
	v_rcp_f32_e32 v71, v71
	v_rcp_f32_e32 v72, v72
	v_rcp_f32_e32 v73, v73
	v_pk_mul_f32 v[70:71], v[26:27], v[70:71]
	s_nop 0
	v_cvt_pk_bf16_f32 v246, v70, v71
	v_pk_mul_f32 v[72:73], v[28:29], v[72:73]
	s_nop 0
	v_cvt_pk_bf16_f32 v247, v72, v73
	s_nop 1
	v_permlane16_swap_b32_e32 v244, v246
	v_permlane16_swap_b32_e32 v245, v247
	v_lshl_add_u64 v[216:217], v[68:69], 0, v[226:227]
	global_store_dwordx4 v[216:217], v[244:247], off
	v_mul_f32_e32 v70, 0xbfb8aa3b, v22
	v_mul_f32_e32 v71, 0xbfb8aa3b, v23
	v_mul_f32_e32 v72, 0xbfb8aa3b, v24
	v_mul_f32_e32 v73, 0xbfb8aa3b, v25
	v_exp_f32_e32 v70, v70
	v_exp_f32_e32 v71, v71
	v_exp_f32_e32 v72, v72
	v_exp_f32_e32 v73, v73
	v_add_f32_e32 v70, 1.0, v70
	v_add_f32_e32 v71, 1.0, v71
	v_add_f32_e32 v72, 1.0, v72
	v_add_f32_e32 v73, 1.0, v73
	v_rcp_f32_e32 v70, v70
	v_rcp_f32_e32 v71, v71
	v_rcp_f32_e32 v72, v72
	v_rcp_f32_e32 v73, v73
	v_lshl_add_u64 v[68:69], v[66:67], 0, s[16:17]
	v_pk_mul_f32 v[70:71], v[22:23], v[70:71]
	s_mov_b32 s16, 0x48000
	v_pk_mul_f32 v[72:73], v[24:25], v[72:73]
	v_cvt_pk_bf16_f32 v248, v70, v71
	v_cvt_pk_bf16_f32 v249, v72, v73
	v_add_co_u32_e32 v72, vcc, s16, v66
	s_mov_b64 s[16:17], 0x50000
	s_nop 0
	v_addc_co_u32_e32 v73, vcc, 0, v67, vcc
	v_mul_f32_e32 v70, 0xbfb8aa3b, v18
	v_mul_f32_e32 v71, 0xbfb8aa3b, v19
	v_mul_f32_e32 v72, 0xbfb8aa3b, v20
	v_mul_f32_e32 v73, 0xbfb8aa3b, v21
	v_exp_f32_e32 v70, v70
	v_exp_f32_e32 v71, v71
	v_exp_f32_e32 v72, v72
	v_exp_f32_e32 v73, v73
	v_add_f32_e32 v70, 1.0, v70
	v_add_f32_e32 v71, 1.0, v71
	v_add_f32_e32 v72, 1.0, v72
	v_add_f32_e32 v73, 1.0, v73
	v_rcp_f32_e32 v70, v70
	v_rcp_f32_e32 v71, v71
	v_rcp_f32_e32 v72, v72
	v_rcp_f32_e32 v73, v73
	v_pk_mul_f32 v[70:71], v[18:19], v[70:71]
	s_nop 0
	v_cvt_pk_bf16_f32 v250, v70, v71
	v_pk_mul_f32 v[72:73], v[20:21], v[72:73]
	s_nop 0
	v_cvt_pk_bf16_f32 v251, v72, v73
	s_nop 1
	v_permlane16_swap_b32_e32 v248, v250
	v_permlane16_swap_b32_e32 v249, v251
	v_lshl_add_u64 v[218:219], v[68:69], 0, v[226:227]
	global_store_dwordx4 v[218:219], v[248:251], off
	v_mul_f32_e32 v70, 0xbfb8aa3b, v14
	v_mul_f32_e32 v71, 0xbfb8aa3b, v15
	v_mul_f32_e32 v72, 0xbfb8aa3b, v16
	v_mul_f32_e32 v73, 0xbfb8aa3b, v17
	v_exp_f32_e32 v70, v70
	v_exp_f32_e32 v71, v71
	v_exp_f32_e32 v72, v72
	v_exp_f32_e32 v73, v73
	v_add_f32_e32 v70, 1.0, v70
	v_add_f32_e32 v71, 1.0, v71
	v_add_f32_e32 v72, 1.0, v72
	v_add_f32_e32 v73, 1.0, v73
	v_rcp_f32_e32 v70, v70
	v_rcp_f32_e32 v71, v71
	v_rcp_f32_e32 v72, v72
	v_rcp_f32_e32 v73, v73
	v_lshl_add_u64 v[68:69], v[66:67], 0, s[16:17]
	v_pk_mul_f32 v[70:71], v[14:15], v[70:71]
	s_mov_b32 s16, 0x50000
	v_pk_mul_f32 v[72:73], v[16:17], v[72:73]
	v_cvt_pk_bf16_f32 v228, v70, v71
	v_cvt_pk_bf16_f32 v229, v72, v73
	v_add_co_u32_e32 v72, vcc, s16, v66
	s_mov_b64 s[16:17], 0x58000
	s_nop 0
	v_addc_co_u32_e32 v73, vcc, 0, v67, vcc
	v_mul_f32_e32 v70, 0xbfb8aa3b, v8
	v_mul_f32_e32 v71, 0xbfb8aa3b, v9
	v_mul_f32_e32 v72, 0xbfb8aa3b, v10
	v_mul_f32_e32 v73, 0xbfb8aa3b, v11
	v_exp_f32_e32 v70, v70
	v_exp_f32_e32 v71, v71
	v_exp_f32_e32 v72, v72
	v_exp_f32_e32 v73, v73
	v_add_f32_e32 v70, 1.0, v70
	v_add_f32_e32 v71, 1.0, v71
	v_add_f32_e32 v72, 1.0, v72
	v_add_f32_e32 v73, 1.0, v73
	v_rcp_f32_e32 v70, v70
	v_rcp_f32_e32 v71, v71
	v_rcp_f32_e32 v72, v72
	v_rcp_f32_e32 v73, v73
	v_pk_mul_f32 v[70:71], v[8:9], v[70:71]
	s_nop 0
	v_cvt_pk_bf16_f32 v230, v70, v71
	v_pk_mul_f32 v[72:73], v[10:11], v[72:73]
	s_nop 0
	v_cvt_pk_bf16_f32 v231, v72, v73
	s_nop 1
	v_permlane16_swap_b32_e32 v228, v230
	v_permlane16_swap_b32_e32 v229, v231
	v_lshl_add_u64 v[214:215], v[68:69], 0, v[226:227]
	global_store_dwordx4 v[214:215], v[228:231], off
	v_mul_f32_e32 v70, 0xbfb8aa3b, v4
	v_mul_f32_e32 v71, 0xbfb8aa3b, v5
	v_mul_f32_e32 v72, 0xbfb8aa3b, v6
	v_mul_f32_e32 v73, 0xbfb8aa3b, v7
	v_exp_f32_e32 v70, v70
	v_exp_f32_e32 v71, v71
	v_exp_f32_e32 v72, v72
	v_exp_f32_e32 v73, v73
	v_add_f32_e32 v70, 1.0, v70
	v_add_f32_e32 v71, 1.0, v71
	v_add_f32_e32 v72, 1.0, v72
	v_add_f32_e32 v73, 1.0, v73
	v_rcp_f32_e32 v70, v70
	v_rcp_f32_e32 v71, v71
	v_rcp_f32_e32 v72, v72
	v_rcp_f32_e32 v73, v73
	v_lshl_add_u64 v[68:69], v[66:67], 0, s[16:17]
	s_mov_b32 s16, 0x58000
	v_pk_mul_f32 v[70:71], v[4:5], v[70:71]
	v_pk_mul_f32 v[72:73], v[6:7], v[72:73]
	v_add_co_u32_e32 v66, vcc, s16, v66
	v_cvt_pk_bf16_f32 v232, v70, v71
	v_cvt_pk_bf16_f32 v233, v72, v73
	v_addc_co_u32_e32 v67, vcc, 0, v67, vcc
	v_mul_f32_e32 v66, 0xbfb8aa3b, v0
	v_mul_f32_e32 v67, 0xbfb8aa3b, v1
	v_mul_f32_e32 v70, 0xbfb8aa3b, v2
	v_mul_f32_e32 v71, 0xbfb8aa3b, v3
	v_exp_f32_e32 v66, v66
	v_exp_f32_e32 v67, v67
	v_exp_f32_e32 v70, v70
	v_exp_f32_e32 v71, v71
	v_add_f32_e32 v66, 1.0, v66
	v_add_f32_e32 v67, 1.0, v67
	v_add_f32_e32 v70, 1.0, v70
	v_add_f32_e32 v71, 1.0, v71
	v_rcp_f32_e32 v66, v66
	v_rcp_f32_e32 v67, v67
	v_rcp_f32_e32 v70, v70
	v_rcp_f32_e32 v71, v71
	v_pk_mul_f32 v[66:67], v[0:1], v[66:67]
	s_nop 0
	v_cvt_pk_bf16_f32 v234, v66, v67
	v_pk_mul_f32 v[70:71], v[2:3], v[70:71]
	s_nop 0
	v_cvt_pk_bf16_f32 v235, v70, v71
	s_nop 1
	v_permlane16_swap_b32_e32 v232, v234
	v_permlane16_swap_b32_e32 v233, v235
	v_lshl_add_u64 v[216:217], v[68:69], 0, v[226:227]
	global_store_dwordx4 v[216:217], v[232:235], off

.LBB0_421:
	s_andn2_b64 vcc, exec, s[60:61]
	s_cbranch_vccnz .LBB0_429
	s_ashr_i32 s60, s41, 1
	s_ashr_i32 s61, s60, 31
	s_lshl_b64 s[16:17], s[60:61], 25
	s_add_u32 s16, s50, s16
	s_addc_u32 s17, s51, s17
	s_cmp_lt_u32 s41, 2
	s_cselect_b64 vcc, -1, 0
	s_and_b32 s25, s53, 0x1e0
	v_mov_b32_e32 v66, 0x3e38aa3b
	v_add_u32_e32 v68, s25, v138
	v_cndmask_b32_e32 v66, 1.0, v66, vcc
	v_ashrrev_i32_e32 v69, 31, v68
	v_lshl_add_u64 v[68:69], v[68:69], 1, s[16:17]
	v_lshlrev_b64 v[70:71], 10, v[136:137]
	s_waitcnt lgkmcnt(0)
	v_pk_mul_f32 v[64:65], v[66:67], v[64:65] op_sel_hi:[0,1]
	v_pk_mul_f32 v[62:63], v[66:67], v[62:63] op_sel_hi:[0,1]
	v_lshl_add_u64 v[68:69], v[68:69], 0, v[70:71]
	v_cvt_pk_bf16_f32 v236, v62, v63
	v_cvt_pk_bf16_f32 v237, v64, v65
	v_pk_mul_f32 v[60:61], v[66:67], v[60:61] op_sel_hi:[0,1]
	v_pk_mul_f32 v[58:59], v[66:67], v[58:59] op_sel_hi:[0,1]
	v_cvt_pk_bf16_f32 v238, v58, v59
	v_cvt_pk_bf16_f32 v239, v60, v61
	s_mov_b64 s[16:17], 0x4000
	s_nop 1
	v_permlane16_swap_b32_e32 v236, v238
	v_permlane16_swap_b32_e32 v237, v239
	v_lshl_add_u64 v[218:219], v[68:69], 0, v[226:227]
	global_store_dwordx4 v[218:219], v[236:239], off
	v_lshl_add_u64 v[70:71], v[68:69], 0, s[16:17]
	s_movk_i32 s16, 0x4000
	v_pk_mul_f32 v[56:57], v[66:67], v[56:57] op_sel_hi:[0,1]
	v_pk_mul_f32 v[54:55], v[66:67], v[54:55] op_sel_hi:[0,1]
	v_add_co_u32_e32 v74, vcc, s16, v68
	v_cvt_pk_bf16_f32 v240, v54, v55
	v_cvt_pk_bf16_f32 v241, v56, v57
	v_addc_co_u32_e32 v75, vcc, 0, v69, vcc
	v_pk_mul_f32 v[52:53], v[66:67], v[52:53] op_sel_hi:[0,1]
	v_pk_mul_f32 v[50:51], v[66:67], v[50:51] op_sel_hi:[0,1]
	v_cvt_pk_bf16_f32 v242, v50, v51
	v_cvt_pk_bf16_f32 v243, v52, v53
	s_mov_b64 s[16:17], 0x8000
	s_nop 1
	v_permlane16_swap_b32_e32 v240, v242
	v_permlane16_swap_b32_e32 v241, v243
	v_lshl_add_u64 v[214:215], v[70:71], 0, v[226:227]
	global_store_dwordx4 v[214:215], v[240:243], off
	v_lshl_add_u64 v[70:71], v[68:69], 0, s[16:17]
	s_mov_b32 s16, 0x8000
	v_pk_mul_f32 v[48:49], v[66:67], v[48:49] op_sel_hi:[0,1]
	v_pk_mul_f32 v[46:47], v[66:67], v[46:47] op_sel_hi:[0,1]
	v_add_co_u32_e32 v74, vcc, s16, v68
	v_cvt_pk_bf16_f32 v244, v46, v47
	v_cvt_pk_bf16_f32 v245, v48, v49
	v_addc_co_u32_e32 v75, vcc, 0, v69, vcc
	v_pk_mul_f32 v[44:45], v[66:67], v[44:45] op_sel_hi:[0,1]
	v_pk_mul_f32 v[42:43], v[66:67], v[42:43] op_sel_hi:[0,1]
	v_cvt_pk_bf16_f32 v246, v42, v43
	v_cvt_pk_bf16_f32 v247, v44, v45
	s_mov_b64 s[16:17], 0xc000
	s_nop 1
	v_permlane16_swap_b32_e32 v244, v246
	v_permlane16_swap_b32_e32 v245, v247
	v_lshl_add_u64 v[216:217], v[70:71], 0, v[226:227]
	global_store_dwordx4 v[216:217], v[244:247], off
	v_lshl_add_u64 v[70:71], v[68:69], 0, s[16:17]
	s_mov_b32 s16, 0xc000
	v_pk_mul_f32 v[40:41], v[66:67], v[40:41] op_sel_hi:[0,1]
	v_pk_mul_f32 v[38:39], v[66:67], v[38:39] op_sel_hi:[0,1]
	v_add_co_u32_e32 v74, vcc, s16, v68
	v_cvt_pk_bf16_f32 v248, v38, v39
	v_cvt_pk_bf16_f32 v249, v40, v41
	v_addc_co_u32_e32 v75, vcc, 0, v69, vcc
	v_pk_mul_f32 v[36:37], v[66:67], v[36:37] op_sel_hi:[0,1]
	v_pk_mul_f32 v[34:35], v[66:67], v[34:35] op_sel_hi:[0,1]
	s_mov_b32 s16, 0x20000
	v_cvt_pk_bf16_f32 v250, v34, v35
	v_cvt_pk_bf16_f32 v251, v36, v37
	v_pk_mul_f32 v[32:33], v[66:67], v[32:33] op_sel_hi:[0,1]
	v_pk_mul_f32 v[30:31], v[66:67], v[30:31] op_sel_hi:[0,1]
	v_add_co_u32_e32 v74, vcc, s16, v68
	s_nop 1
	v_permlane16_swap_b32_e32 v248, v250
	v_permlane16_swap_b32_e32 v249, v251
	v_lshl_add_u64 v[218:219], v[70:71], 0, v[226:227]
	global_store_dwordx4 v[218:219], v[248:251], off
	v_cvt_pk_bf16_f32 v228, v30, v31
	v_cvt_pk_bf16_f32 v229, v32, v33
	v_addc_co_u32_e32 v75, vcc, 0, v69, vcc
	v_pk_mul_f32 v[28:29], v[66:67], v[28:29] op_sel_hi:[0,1]
	v_pk_mul_f32 v[26:27], v[66:67], v[26:27] op_sel_hi:[0,1]
	v_lshl_add_u64 v[70:71], v[68:69], 0, s[46:47]
	v_cvt_pk_bf16_f32 v230, v26, v27
	v_cvt_pk_bf16_f32 v231, v28, v29
	s_mov_b64 s[16:17], 0x24000
	s_nop 1
	v_permlane16_swap_b32_e32 v228, v230
	v_permlane16_swap_b32_e32 v229, v231
	v_lshl_add_u64 v[214:215], v[70:71], 0, v[226:227]
	global_store_dwordx4 v[214:215], v[228:231], off
	v_lshl_add_u64 v[70:71], v[68:69], 0, s[16:17]
	s_mov_b32 s16, 0x24000
	v_pk_mul_f32 v[24:25], v[66:67], v[24:25] op_sel_hi:[0,1]
	v_pk_mul_f32 v[22:23], v[66:67], v[22:23] op_sel_hi:[0,1]
	v_add_co_u32_e32 v74, vcc, s16, v68
	v_cvt_pk_bf16_f32 v232, v22, v23
	v_cvt_pk_bf16_f32 v233, v24, v25
	v_addc_co_u32_e32 v75, vcc, 0, v69, vcc
	v_pk_mul_f32 v[20:21], v[66:67], v[20:21] op_sel_hi:[0,1]
	v_pk_mul_f32 v[18:19], v[66:67], v[18:19] op_sel_hi:[0,1]
	v_cvt_pk_bf16_f32 v234, v18, v19
	v_cvt_pk_bf16_f32 v235, v20, v21
	s_mov_b64 s[16:17], 0x28000
	s_nop 1
	v_permlane16_swap_b32_e32 v232, v234
	v_permlane16_swap_b32_e32 v233, v235
	v_lshl_add_u64 v[216:217], v[70:71], 0, v[226:227]
	global_store_dwordx4 v[216:217], v[232:235], off
	v_lshl_add_u64 v[70:71], v[68:69], 0, s[16:17]
	s_mov_b32 s16, 0x28000
	v_pk_mul_f32 v[16:17], v[66:67], v[16:17] op_sel_hi:[0,1]
	v_pk_mul_f32 v[14:15], v[66:67], v[14:15] op_sel_hi:[0,1]
	v_add_co_u32_e32 v74, vcc, s16, v68
	v_cvt_pk_bf16_f32 v236, v14, v15
	v_cvt_pk_bf16_f32 v237, v16, v17
	v_addc_co_u32_e32 v75, vcc, 0, v69, vcc
	v_pk_mul_f32 v[10:11], v[66:67], v[10:11] op_sel_hi:[0,1]
	v_pk_mul_f32 v[8:9], v[66:67], v[8:9] op_sel_hi:[0,1]
	v_cvt_pk_bf16_f32 v238, v8, v9
	v_cvt_pk_bf16_f32 v239, v10, v11
	s_mov_b64 s[16:17], 0x2c000
	s_nop 1
	v_permlane16_swap_b32_e32 v236, v238
	v_permlane16_swap_b32_e32 v237, v239
	v_lshl_add_u64 v[218:219], v[70:71], 0, v[226:227]
	global_store_dwordx4 v[218:219], v[236:239], off
	v_lshl_add_u64 v[70:71], v[68:69], 0, s[16:17]
	s_mov_b32 s16, 0x2c000
	v_pk_mul_f32 v[6:7], v[66:67], v[6:7] op_sel_hi:[0,1]
	v_pk_mul_f32 v[4:5], v[66:67], v[4:5] op_sel_hi:[0,1]
	v_add_co_u32_e32 v68, vcc, s16, v68
	v_pk_mul_f32 v[2:3], v[66:67], v[2:3] op_sel_hi:[0,1]
	v_pk_mul_f32 v[0:1], v[66:67], v[0:1] op_sel_hi:[0,1]
	v_cvt_pk_bf16_f32 v240, v4, v5
	v_cvt_pk_bf16_f32 v241, v6, v7
	v_addc_co_u32_e32 v69, vcc, 0, v69, vcc
	v_cvt_pk_bf16_f32 v242, v0, v1
	v_cvt_pk_bf16_f32 v243, v2, v3
	s_cmp_gt_i32 s60, 1
	s_nop 1
	v_permlane16_swap_b32_e32 v240, v242
	v_permlane16_swap_b32_e32 v241, v243
	v_lshl_add_u64 v[214:215], v[70:71], 0, v[226:227]
	global_store_dwordx4 v[214:215], v[240:243], off
	s_cbranch_scc1 .LBB0_429
	v_mul_f32_e32 v63, v63, v63
	v_mul_f32_e32 v59, v59, v59
	v_mul_f32_e32 v55, v55, v55
	v_mul_f32_e32 v51, v51, v51
	v_fmac_f32_e32 v63, v62, v62
	v_mul_f32_e32 v62, v65, v65
	v_fmac_f32_e32 v59, v58, v58
	v_mul_f32_e32 v58, v61, v61
	v_fmac_f32_e32 v55, v54, v54
	v_mul_f32_e32 v54, v57, v57
	v_fmac_f32_e32 v51, v50, v50
	v_mul_f32_e32 v50, v53, v53
	v_mul_f32_e32 v47, v47, v47
	v_mul_f32_e32 v43, v43, v43
	v_mul_f32_e32 v39, v39, v39
	v_mul_f32_e32 v35, v35, v35
	v_fmac_f32_e32 v62, v64, v64
	v_fmac_f32_e32 v58, v60, v60
	v_fmac_f32_e32 v54, v56, v56
	v_fmac_f32_e32 v50, v52, v52
	v_fmac_f32_e32 v47, v46, v46
	v_mul_f32_e32 v46, v49, v49
	v_fmac_f32_e32 v43, v42, v42
	v_mul_f32_e32 v42, v45, v45
	v_fmac_f32_e32 v39, v38, v38
	v_mul_f32_e32 v38, v41, v41
	v_fmac_f32_e32 v35, v34, v34
	v_mul_f32_e32 v34, v37, v37
	v_mul_f32_e32 v31, v31, v31
	v_mul_f32_e32 v27, v27, v27
	v_mul_f32_e32 v23, v23, v23
	v_mul_f32_e32 v19, v19, v19
	v_add_f32_e32 v62, v63, v62
	v_add_f32_e32 v58, v59, v58
	v_add_f32_e32 v54, v55, v54
	v_add_f32_e32 v50, v51, v50
	v_fmac_f32_e32 v46, v48, v48
	v_fmac_f32_e32 v42, v44, v44
	v_fmac_f32_e32 v38, v40, v40
	v_fmac_f32_e32 v34, v36, v36
	v_fmac_f32_e32 v31, v30, v30
	v_mul_f32_e32 v30, v33, v33
	v_fmac_f32_e32 v27, v26, v26
	v_mul_f32_e32 v26, v29, v29
	v_fmac_f32_e32 v23, v22, v22
	v_mul_f32_e32 v22, v25, v25
	v_fmac_f32_e32 v19, v18, v18
	v_mul_f32_e32 v18, v21, v21
	v_mul_f32_e32 v15, v15, v15
	v_mul_f32_e32 v9, v9, v9
	v_mul_f32_e32 v5, v5, v5
	v_mul_f32_e32 v1, v1, v1
	v_add_f32_e32 v58, v62, v58
	v_add_f32_e32 v50, v54, v50
	v_add_f32_e32 v46, v47, v46
	v_add_f32_e32 v42, v43, v42
	v_add_f32_e32 v38, v39, v38
	v_add_f32_e32 v34, v35, v34
	v_fmac_f32_e32 v30, v32, v32
	v_fmac_f32_e32 v26, v28, v28
	v_fmac_f32_e32 v22, v24, v24
	v_fmac_f32_e32 v18, v20, v20
	v_fmac_f32_e32 v15, v14, v14
	v_mul_f32_e32 v14, v17, v17
	v_fmac_f32_e32 v9, v8, v8
	v_mul_f32_e32 v8, v11, v11
	v_fmac_f32_e32 v5, v4, v4
	v_mul_f32_e32 v4, v7, v7
	v_fmac_f32_e32 v1, v0, v0
	v_mul_f32_e32 v0, v3, v3
	ds_bpermute_b32 v59, v155, v58
	ds_bpermute_b32 v51, v155, v50
	v_add_f32_e32 v42, v46, v42
	v_add_f32_e32 v34, v38, v34
	v_add_f32_e32 v30, v31, v30
	v_add_f32_e32 v26, v27, v26
	v_add_f32_e32 v22, v23, v22
	v_add_f32_e32 v18, v19, v18
	v_fmac_f32_e32 v14, v16, v16
	v_fmac_f32_e32 v8, v10, v10
	v_fmac_f32_e32 v4, v6, v6
	v_fmac_f32_e32 v0, v2, v2
	ds_bpermute_b32 v43, v155, v42
	ds_bpermute_b32 v35, v155, v34
	v_add_f32_e32 v26, v30, v26
	v_add_f32_e32 v18, v22, v18
	v_add_f32_e32 v14, v15, v14
	v_add_f32_e32 v8, v9, v8
	v_add_f32_e32 v4, v5, v4
	v_add_f32_e32 v0, v1, v0
	ds_bpermute_b32 v27, v155, v26
	ds_bpermute_b32 v19, v155, v18
	v_add_f32_e32 v8, v14, v8
	v_add_f32_e32 v0, v4, v0
	ds_bpermute_b32 v9, v155, v8
	ds_bpermute_b32 v1, v155, v0
	s_waitcnt lgkmcnt(0)
	v_add_f32_e32 v52, v58, v59
	v_add_f32_e32 v50, v50, v51
	ds_bpermute_b32 v53, v154, v52
	ds_bpermute_b32 v51, v154, v50
	v_add_f32_e32 v38, v42, v43
	v_add_f32_e32 v34, v34, v35
	ds_bpermute_b32 v39, v154, v38
	ds_bpermute_b32 v35, v154, v34
	v_add_f32_e32 v26, v26, v27
	v_add_f32_e32 v2, v18, v19
	ds_bpermute_b32 v27, v154, v26
	ds_bpermute_b32 v3, v154, v2
	v_add_f32_e32 v4, v8, v9
	v_add_f32_e32 v0, v0, v1
	ds_bpermute_b32 v5, v154, v4
	ds_bpermute_b32 v1, v154, v0
	s_waitcnt lgkmcnt(0)
	v_add_f32_e32 v36, v52, v53
	v_add_f32_e32 v37, v50, v51
	v_max3_f32 v28, v36, 0, v37
	v_add_f32_e32 v29, v38, v39
	v_add_f32_e32 v30, v34, v35
	v_max3_f32 v28, v28, v29, v30
	v_add_f32_e32 v6, v26, v27
	v_add_f32_e32 v2, v2, v3
	v_max3_f32 v2, v28, v6, v2
	v_add_f32_e32 v3, v4, v5
	v_add_f32_e32 v0, v0, v1
	v_max3_f32 v0, v2, v3, v0
	ds_bpermute_b32 v1, v157, v0
	s_waitcnt lgkmcnt(0)
	v_max_f32_e32 v1, v1, v1
	v_max_f32_e32 v0, v0, v1
	ds_bpermute_b32 v1, v149, v0
	s_waitcnt lgkmcnt(0)
	v_max_f32_e32 v1, v1, v1
	v_max_f32_e32 v0, v0, v1
	ds_bpermute_b32 v1, v148, v0
	s_waitcnt lgkmcnt(0)
	v_max_f32_e32 v1, v1, v1
	v_max_f32_e32 v0, v0, v1
	ds_bpermute_b32 v1, v156, v0
	s_and_saveexec_b64 s[62:63], s[4:5]
	s_cbranch_execz .LBB0_428
	s_waitcnt lgkmcnt(0)
	v_max_f32_e32 v1, v1, v1
	v_max_f32_e32 v0, v0, v0
	s_mov_b64 s[4:5], exec
	v_max_f32_e32 v0, v0, v1
	s_mov_b32 s16, 0

.LBB0_572:
	v_mbcnt_lo_u32_b32 v176, -1, 0
	v_mbcnt_hi_u32_b32 v176, -1, v176
	v_and_b32_e32 v176, 16, v176
	v_lshrrev_b32_e32 v177, 1, v176
	v_add_u32_e32 v176, v176, v177
	v_mov_b32_e32 v177, 0
	s_lshl_b32 s6, s74, 8
	v_mov_b32_e32 v130, v252
	v_mov_b32_e32 v149, v221
	s_add_i32 s6, s6, s41
	s_brev_b32 s16, 60
	v_add_u32_e32 v144, s6, v130
	v_ashrrev_i32_e32 v145, 31, v144
	v_lshl_add_u64 v[130:131], v[144:145], 4, s[88:89]
	global_load_dwordx4 v[206:209], v[130:131], off
	global_load_dwordx4 v[210:213], v[130:131], off offset:256
	global_load_dwordx4 v[214:217], v[130:131], off offset:512
	global_load_dwordx4 v[222:225], v[130:131], off offset:768
	global_load_dwordx4 v[226:229], v[130:131], off offset:2048
	global_load_dwordx4 v[230:233], v[130:131], off offset:2304
	global_load_dwordx4 v[234:237], v[130:131], off offset:2560
	global_load_dwordx4 v[238:241], v[130:131], off offset:2816
	v_add_u32_e32 v146, 16, v144
	v_ashrrev_i32_e32 v147, 31, v146
	s_mov_b32 s6, 0x358637bd
	v_mov_b64_e32 v[150:151], s[6:7]
	v_add_u32_e32 v154, 32, v144
	v_ashrrev_i32_e32 v155, 31, v154
	v_add_u32_e32 v156, 48, v144
	v_ashrrev_i32_e32 v157, 31, v156
	v_add_u32_e32 v160, 0x90, v144
	v_ashrrev_i32_e32 v161, 31, v160
	s_waitcnt vmcnt(7)
	v_mov_b32_e32 v130, v206
	v_mov_b32_e32 v131, v207
	v_mov_b32_e32 v132, v208
	v_mov_b32_e32 v133, v209
	v_mov_b32_e32 v136, v131
	v_mov_b32_e32 v137, v132
	v_mov_b32_e32 v131, v133
	v_pk_add_f32 v[136:137], v[136:137], v[130:131]
	v_lshl_add_u64 v[130:131], v[146:147], 4, s[88:89]
	s_waitcnt vmcnt(6)
	v_mov_b32_e32 v130, v210
	v_mov_b32_e32 v131, v211
	v_mov_b32_e32 v132, v212
	v_mov_b32_e32 v133, v213
	v_mov_b32_e32 v138, v131
	v_mov_b32_e32 v139, v132
	v_mov_b32_e32 v131, v133
	v_pk_add_f32 v[130:131], v[138:139], v[130:131]
	v_mov_b32_e32 v133, v136
	v_mov_b32_e32 v132, v130
	v_mov_b32_e32 v136, v131
	v_pk_add_f32 v[130:131], v[132:133], v[136:137]
	s_nop 0
	v_pk_fma_f32 v[130:131], v[130:131], s[16:17], v[150:151] op_sel_hi:[1,0,0]
	s_nop 0
	v_mul_f32_e32 v132, 0x4b800000, v131
	v_cmp_gt_f32_e64 s[6:7], s29, v131
	v_cmp_gt_f32_e32 vcc, s29, v130
	s_nop 0
	v_cndmask_b32_e64 v131, v131, v132, s[6:7]
	v_rsq_f32_e32 v131, v131
	s_nop 0
	v_mul_f32_e32 v132, 0x45800000, v131
	v_cndmask_b32_e64 v138, v131, v132, s[6:7]
	v_mul_f32_e32 v131, 0x4b800000, v130
	v_cndmask_b32_e32 v130, v130, v131, vcc
	v_rsq_f32_e32 v130, v130
	v_pk_mul_f32 v[124:125], v[124:125], v[138:139] op_sel_hi:[1,0]
	v_pk_mul_f32 v[122:123], v[122:123], v[138:139] op_sel_hi:[1,0]
	v_pk_mul_f32 v[128:129], v[128:129], v[138:139] op_sel_hi:[1,0]
	v_mul_f32_e32 v131, 0x45800000, v130
	v_cndmask_b32_e32 v136, v130, v131, vcc
	v_lshl_add_u64 v[130:131], v[154:155], 4, s[88:89]
	v_cvt_pk_bf16_f32 v122, v122, v123
	v_cvt_pk_bf16_f32 v123, v124, v125
	v_pk_mul_f32 v[108:109], v[108:109], v[136:137] op_sel_hi:[1,0]
	v_pk_mul_f32 v[106:107], v[106:107], v[136:137] op_sel_hi:[1,0]
	v_pk_mul_f32 v[126:127], v[126:127], v[138:139] op_sel_hi:[1,0]
	v_cvt_pk_bf16_f32 v106, v106, v107
	v_cvt_pk_bf16_f32 v107, v108, v109
	v_pk_mul_f32 v[112:113], v[112:113], v[136:137] op_sel_hi:[1,0]
	v_pk_mul_f32 v[110:111], v[110:111], v[136:137] op_sel_hi:[1,0]
	v_pk_mul_f32 v[56:57], v[56:57], v[138:139] op_sel_hi:[1,0]
	v_pk_mul_f32 v[54:55], v[54:55], v[138:139] op_sel_hi:[1,0]
	v_cvt_pk_bf16_f32 v126, v126, v127
	v_cvt_pk_bf16_f32 v127, v128, v129
	v_cvt_pk_bf16_f32 v110, v110, v111
	v_cvt_pk_bf16_f32 v111, v112, v113
	v_cvt_pk_bf16_f32 v54, v54, v55
	v_cvt_pk_bf16_f32 v55, v56, v57
	v_pk_mul_f32 v[40:41], v[40:41], v[136:137] op_sel_hi:[1,0]
	v_pk_mul_f32 v[38:39], v[38:39], v[136:137] op_sel_hi:[1,0]
	v_pk_mul_f32 v[64:65], v[64:65], v[138:139] op_sel_hi:[1,0]
	v_cvt_pk_bf16_f32 v38, v38, v39
	v_cvt_pk_bf16_f32 v39, v40, v41
	v_pk_mul_f32 v[62:63], v[62:63], v[138:139] op_sel_hi:[1,0]
	v_pk_mul_f32 v[48:49], v[48:49], v[136:137] op_sel_hi:[1,0]
	v_pk_mul_f32 v[46:47], v[46:47], v[136:137] op_sel_hi:[1,0]
	v_cvt_pk_bf16_f32 v62, v62, v63
	v_cvt_pk_bf16_f32 v63, v64, v65
	v_cvt_pk_bf16_f32 v46, v46, v47
	v_cvt_pk_bf16_f32 v47, v48, v49
	s_waitcnt vmcnt(5)
	v_mov_b32_e32 v130, v214
	v_mov_b32_e32 v131, v215
	v_mov_b32_e32 v132, v216
	v_mov_b32_e32 v133, v217
	v_mov_b32_e32 v152, v131
	v_mov_b32_e32 v153, v132
	v_mov_b32_e32 v131, v133
	v_pk_add_f32 v[152:153], v[152:153], v[130:131]
	v_lshl_add_u64 v[130:131], v[156:157], 4, s[88:89]
	s_waitcnt vmcnt(4)
	v_mov_b32_e32 v130, v222
	v_mov_b32_e32 v131, v223
	v_mov_b32_e32 v132, v224
	v_mov_b32_e32 v133, v225
	v_mov_b32_e32 v158, v131
	v_mov_b32_e32 v159, v132
	v_mov_b32_e32 v131, v133
	v_pk_add_f32 v[130:131], v[158:159], v[130:131]
	v_mov_b32_e32 v133, v152
	v_mov_b32_e32 v132, v130
	v_mov_b32_e32 v152, v131
	v_pk_add_f32 v[130:131], v[132:133], v[152:153]
	v_add_u32_e32 v158, 0x80, v144
	v_pk_fma_f32 v[130:131], v[130:131], s[16:17], v[150:151] op_sel_hi:[1,0,0]
	v_ashrrev_i32_e32 v159, 31, v158
	v_mul_f32_e32 v132, 0x4b800000, v131
	v_cmp_gt_f32_e64 s[6:7], s29, v131
	v_cmp_gt_f32_e32 vcc, s29, v130
	s_nop 0
	v_cndmask_b32_e64 v131, v131, v132, s[6:7]
	v_rsq_f32_e32 v131, v131
	s_nop 0
	v_mul_f32_e32 v132, 0x45800000, v131
	v_cndmask_b32_e64 v142, v131, v132, s[6:7]
	v_mul_f32_e32 v131, 0x4b800000, v130
	v_cndmask_b32_e32 v130, v130, v131, vcc
	v_rsq_f32_e32 v130, v130
	v_pk_mul_f32 v[92:93], v[92:93], v[142:143] op_sel_hi:[1,0]
	v_pk_mul_f32 v[90:91], v[90:91], v[142:143] op_sel_hi:[1,0]
	v_pk_mul_f32 v[96:97], v[96:97], v[142:143] op_sel_hi:[1,0]
	v_mul_f32_e32 v131, 0x45800000, v130
	v_cndmask_b32_e32 v140, v130, v131, vcc
	v_lshl_add_u64 v[130:131], v[158:159], 4, s[88:89]
	v_cvt_pk_bf16_f32 v90, v90, v91
	v_cvt_pk_bf16_f32 v91, v92, v93
	v_pk_mul_f32 v[80:81], v[80:81], v[140:141] op_sel_hi:[1,0]
	v_pk_mul_f32 v[78:79], v[78:79], v[140:141] op_sel_hi:[1,0]
	v_pk_mul_f32 v[76:77], v[76:77], v[140:141] op_sel_hi:[1,0]
	v_pk_mul_f32 v[74:75], v[74:75], v[140:141] op_sel_hi:[1,0]
	v_cvt_pk_bf16_f32 v180, v78, v79
	v_cvt_pk_bf16_f32 v181, v80, v81
	v_cvt_pk_bf16_f32 v182, v74, v75
	v_cvt_pk_bf16_f32 v183, v76, v77
	v_pk_mul_f32 v[94:95], v[94:95], v[142:143] op_sel_hi:[1,0]
	v_pk_mul_f32 v[24:25], v[24:25], v[142:143] op_sel_hi:[1,0]
	v_cvt_pk_bf16_f32 v94, v94, v95
	v_cvt_pk_bf16_f32 v95, v96, v97
	v_pk_mul_f32 v[22:23], v[22:23], v[142:143] op_sel_hi:[1,0]
	v_pk_mul_f32 v[16:17], v[16:17], v[140:141] op_sel_hi:[1,0]
	v_cvt_pk_bf16_f32 v22, v22, v23
	v_cvt_pk_bf16_f32 v23, v24, v25
	v_pk_mul_f32 v[14:15], v[14:15], v[140:141] op_sel_hi:[1,0]
	v_pk_mul_f32 v[6:7], v[6:7], v[140:141] op_sel_hi:[1,0]
	v_cvt_pk_bf16_f32 v200, v14, v15
	v_cvt_pk_bf16_f32 v201, v16, v17
	v_pk_mul_f32 v[4:5], v[4:5], v[140:141] op_sel_hi:[1,0]
	v_pk_mul_f32 v[32:33], v[32:33], v[142:143] op_sel_hi:[1,0]
	v_cvt_pk_bf16_f32 v202, v4, v5
	v_cvt_pk_bf16_f32 v203, v6, v7
	v_pk_mul_f32 v[30:31], v[30:31], v[142:143] op_sel_hi:[1,0]
	s_waitcnt vmcnt(3)
	v_mov_b32_e32 v130, v226
	v_mov_b32_e32 v131, v227
	v_mov_b32_e32 v132, v228
	v_mov_b32_e32 v133, v229
	v_mov_b32_e32 v152, v131
	v_mov_b32_e32 v153, v132
	v_mov_b32_e32 v131, v133
	v_pk_add_f32 v[152:153], v[152:153], v[130:131]
	v_lshl_add_u64 v[130:131], v[160:161], 4, s[88:89]
	v_cvt_pk_bf16_f32 v30, v30, v31
	v_cvt_pk_bf16_f32 v31, v32, v33
	s_waitcnt vmcnt(2)
	v_mov_b32_e32 v130, v230
	v_mov_b32_e32 v131, v231
	v_mov_b32_e32 v132, v232
	v_mov_b32_e32 v133, v233
	v_mov_b32_e32 v162, v131
	v_mov_b32_e32 v163, v132
	v_mov_b32_e32 v131, v133
	v_pk_add_f32 v[130:131], v[162:163], v[130:131]
	v_mov_b32_e32 v133, v152
	v_mov_b32_e32 v132, v130
	v_mov_b32_e32 v152, v131
	v_pk_add_f32 v[130:131], v[132:133], v[152:153]
	v_add_u32_e32 v162, 0xa0, v144
	v_pk_fma_f32 v[130:131], v[130:131], s[16:17], v[150:151] op_sel_hi:[1,0,0]
	v_ashrrev_i32_e32 v163, 31, v162
	v_mul_f32_e32 v132, 0x4b800000, v131
	v_cmp_gt_f32_e64 s[6:7], s29, v131
	v_cmp_gt_f32_e32 vcc, s29, v130
	s_nop 0
	v_cndmask_b32_e64 v131, v131, v132, s[6:7]
	v_rsq_f32_e32 v131, v131
	s_nop 0
	v_mul_f32_e32 v132, 0x45800000, v131
	v_cndmask_b32_e64 v152, v131, v132, s[6:7]
	v_mul_f32_e32 v131, 0x4b800000, v130
	v_cndmask_b32_e32 v130, v130, v131, vcc
	v_rsq_f32_e32 v130, v130
	v_pk_mul_f32 v[80:81], v[118:119], v[152:153] op_sel_hi:[1,0]
	v_pk_mul_f32 v[6:7], v[60:61], v[152:153] op_sel_hi:[1,0]
	v_cvt_pk_bf16_f32 v184, v80, v81
	v_mul_f32_e32 v131, 0x45800000, v130
	v_cndmask_b32_e32 v148, v130, v131, vcc
	v_lshl_add_u64 v[130:131], v[162:163], 4, s[88:89]
	s_waitcnt vmcnt(1)
	v_mov_b32_e32 v130, v234
	v_mov_b32_e32 v131, v235
	v_mov_b32_e32 v132, v236
	v_mov_b32_e32 v133, v237
	v_mov_b32_e32 v164, v131
	v_mov_b32_e32 v165, v132
	v_mov_b32_e32 v131, v133
	v_pk_add_f32 v[178:179], v[164:165], v[130:131]
	v_add_u32_e32 v164, 0xb0, v144
	v_ashrrev_i32_e32 v165, 31, v164
	v_lshl_add_u64 v[130:131], v[164:165], 4, s[88:89]
	v_lshlrev_b64 v[144:145], 10, v[144:145]
	s_waitcnt vmcnt(0)
	v_mov_b32_e32 v130, v238
	v_mov_b32_e32 v131, v239
	v_mov_b32_e32 v132, v240
	v_mov_b32_e32 v133, v241
	v_mov_b32_e32 v168, v131
	v_mov_b32_e32 v169, v132
	v_mov_b32_e32 v131, v133
	v_pk_add_f32 v[130:131], v[168:169], v[130:131]
	v_mov_b32_e32 v133, v178
	v_mov_b32_e32 v132, v130
	v_mov_b32_e32 v178, v131
	v_pk_add_f32 v[130:131], v[132:133], v[178:179]
	s_nop 0
	v_pk_fma_f32 v[132:133], v[130:131], s[16:17], v[150:151] op_sel_hi:[1,0,0]
	s_nop 0
	v_mul_f32_e32 v130, 0x4b800000, v133
	v_cmp_gt_f32_e64 s[6:7], s29, v133
	v_cmp_gt_f32_e32 vcc, s29, v132
	s_nop 0
	v_cndmask_b32_e64 v130, v133, v130, s[6:7]
	v_rsq_f32_e32 v130, v130
	s_nop 0
	v_mul_f32_e32 v131, 0x45800000, v130
	v_cndmask_b32_e64 v130, v130, v131, s[6:7]
	s_lshl_b32 s6, s67, 7
	s_or_b32 s6, s6, s66
	v_lshl_add_u32 v150, v149, 2, s6
	v_ashrrev_i32_e32 v151, 31, v150
	v_lshl_add_u64 v[168:169], v[150:151], 1, s[12:13]
	v_lshl_add_u64 v[170:171], v[168:169], 0, v[144:145]
	global_store_dwordx2 v[170:171], v[122:123], off offset:32
	v_lshlrev_b64 v[122:123], 10, v[146:147]
	v_lshl_add_u64 v[124:125], v[168:169], 0, v[122:123]
	global_store_dwordx2 v[124:125], v[106:107], off offset:32
	v_lshlrev_b64 v[106:107], 10, v[154:155]
	v_lshl_add_u64 v[108:109], v[168:169], 0, v[106:107]
	global_store_dwordx2 v[108:109], v[90:91], off offset:32
	v_lshlrev_b64 v[90:91], 10, v[156:157]
	v_lshl_add_u64 v[92:93], v[168:169], 0, v[90:91]
	s_nop 1
	v_permlane16_swap_b32_e32 v180, v182
	v_permlane16_swap_b32_e32 v181, v183
	v_lshl_add_u64 v[204:205], v[92:93], 0, v[176:177]
	global_store_dwordx4 v[204:205], v[180:183], off
	v_lshlrev_b64 v[74:75], 10, v[158:159]
	v_pk_mul_f32 v[78:79], v[120:121], v[152:153] op_sel_hi:[1,0]
	v_lshl_add_u64 v[76:77], v[168:169], 0, v[74:75]
	v_cvt_pk_bf16_f32 v185, v78, v79
	v_mul_f32_e32 v131, 0x4b800000, v132
	v_pk_mul_f32 v[78:79], v[116:117], v[152:153] op_sel_hi:[1,0]
	v_pk_mul_f32 v[80:81], v[114:115], v[152:153] op_sel_hi:[1,0]
	v_cndmask_b32_e32 v131, v132, v131, vcc
	v_cvt_pk_bf16_f32 v186, v80, v81
	v_cvt_pk_bf16_f32 v187, v78, v79
	v_rsq_f32_e32 v131, v131
	s_nop 1
	v_permlane16_swap_b32_e32 v184, v186
	v_permlane16_swap_b32_e32 v185, v187
	v_lshl_add_u64 v[218:219], v[76:77], 0, v[176:177]
	global_store_dwordx4 v[218:219], v[184:187], off
	v_lshlrev_b64 v[76:77], 10, v[160:161]
	v_pk_mul_f32 v[80:81], v[104:105], v[148:149] op_sel_hi:[1,0]
	v_pk_mul_f32 v[92:93], v[102:103], v[148:149] op_sel_hi:[1,0]
	v_lshl_add_u64 v[78:79], v[168:169], 0, v[76:77]
	v_cvt_pk_bf16_f32 v188, v92, v93
	v_cvt_pk_bf16_f32 v189, v80, v81
	v_pk_mul_f32 v[80:81], v[100:101], v[148:149] op_sel_hi:[1,0]
	v_pk_mul_f32 v[92:93], v[98:99], v[148:149] op_sel_hi:[1,0]
	v_mul_f32_e32 v132, 0x45800000, v131
	v_cvt_pk_bf16_f32 v190, v92, v93
	v_cvt_pk_bf16_f32 v191, v80, v81
	s_nop 1
	v_permlane16_swap_b32_e32 v188, v190
	v_permlane16_swap_b32_e32 v189, v191
	v_lshl_add_u64 v[242:243], v[78:79], 0, v[176:177]
	global_store_dwordx4 v[242:243], v[188:191], off
	v_lshlrev_b64 v[78:79], 10, v[162:163]
	v_pk_mul_f32 v[88:89], v[88:89], v[130:131] op_sel_hi:[1,0]
	v_pk_mul_f32 v[86:87], v[86:87], v[130:131] op_sel_hi:[1,0]
	v_pk_mul_f32 v[84:85], v[84:85], v[130:131] op_sel_hi:[1,0]
	v_pk_mul_f32 v[82:83], v[82:83], v[130:131] op_sel_hi:[1,0]
	v_cndmask_b32_e32 v132, v131, v132, vcc
	v_lshl_add_u64 v[80:81], v[168:169], 0, v[78:79]
	v_cvt_pk_bf16_f32 v192, v86, v87
	v_cvt_pk_bf16_f32 v193, v88, v89
	v_cvt_pk_bf16_f32 v194, v82, v83
	v_cvt_pk_bf16_f32 v195, v84, v85
	s_nop 1
	v_permlane16_swap_b32_e32 v192, v194
	v_permlane16_swap_b32_e32 v193, v195
	v_lshl_add_u64 v[172:173], v[80:81], 0, v[176:177]
	global_store_dwordx4 v[172:173], v[192:195], off
	v_lshlrev_b64 v[80:81], 10, v[164:165]
	v_pk_mul_f32 v[68:69], v[68:69], v[132:133] op_sel_hi:[1,0]
	v_pk_mul_f32 v[66:67], v[66:67], v[132:133] op_sel_hi:[1,0]
	v_lshl_add_u64 v[82:83], v[168:169], 0, v[80:81]
	v_cvt_pk_bf16_f32 v198, v66, v67
	v_cvt_pk_bf16_f32 v199, v68, v69
	v_add_u32_e32 v66, 64, v150
	v_ashrrev_i32_e32 v67, 31, v66
	v_pk_mul_f32 v[72:73], v[72:73], v[132:133] op_sel_hi:[1,0]
	v_pk_mul_f32 v[70:71], v[70:71], v[132:133] op_sel_hi:[1,0]
	v_lshl_add_u64 v[66:67], v[66:67], 1, s[12:13]
	v_cvt_pk_bf16_f32 v196, v70, v71
	v_cvt_pk_bf16_f32 v197, v72, v73
	v_lshl_add_u64 v[68:69], v[66:67], 0, v[144:145]
	global_store_dwordx2 v[170:171], v[126:127], off
	global_store_dwordx2 v[124:125], v[110:111], off
	global_store_dwordx2 v[108:109], v[94:95], off
	s_nop 1
	v_permlane16_swap_b32_e32 v196, v198
	v_permlane16_swap_b32_e32 v197, v199
	v_lshl_add_u64 v[174:175], v[82:83], 0, v[176:177]
	global_store_dwordx4 v[174:175], v[196:199], off
	global_store_dwordx2 v[68:69], v[54:55], off offset:32
	v_lshl_add_u64 v[54:55], v[66:67], 0, v[122:123]
	global_store_dwordx2 v[54:55], v[38:39], off offset:32
	v_lshl_add_u64 v[38:39], v[66:67], 0, v[106:107]
	global_store_dwordx2 v[38:39], v[22:23], off offset:32
	v_lshl_add_u64 v[22:23], v[66:67], 0, v[90:91]
	v_pk_mul_f32 v[14:15], v[58:59], v[152:153] op_sel_hi:[1,0]
	s_nop 1
	v_permlane16_swap_b32_e32 v200, v202
	v_permlane16_swap_b32_e32 v201, v203
	v_lshl_add_u64 v[204:205], v[22:23], 0, v[176:177]
	global_store_dwordx4 v[204:205], v[200:203], off
	v_lshl_add_u64 v[4:5], v[66:67], 0, v[74:75]
	v_cvt_pk_bf16_f32 v244, v14, v15
	v_cvt_pk_bf16_f32 v245, v6, v7
	v_pk_mul_f32 v[6:7], v[52:53], v[152:153] op_sel_hi:[1,0]
	v_pk_mul_f32 v[14:15], v[50:51], v[152:153] op_sel_hi:[1,0]
	v_pk_mul_f32 v[8:9], v[8:9], v[132:133] op_sel_hi:[1,0]
	v_cvt_pk_bf16_f32 v246, v14, v15
	v_cvt_pk_bf16_f32 v247, v6, v7
	s_nop 1
	v_permlane16_swap_b32_e32 v244, v246
	v_permlane16_swap_b32_e32 v245, v247
	v_lshl_add_u64 v[218:219], v[4:5], 0, v[176:177]
	global_store_dwordx4 v[218:219], v[244:247], off
	v_pk_mul_f32 v[6:7], v[44:45], v[148:149] op_sel_hi:[1,0]
	v_pk_mul_f32 v[14:15], v[42:43], v[148:149] op_sel_hi:[1,0]
	v_lshl_add_u64 v[4:5], v[66:67], 0, v[76:77]
	v_cvt_pk_bf16_f32 v248, v14, v15
	v_cvt_pk_bf16_f32 v249, v6, v7
	v_pk_mul_f32 v[6:7], v[36:37], v[148:149] op_sel_hi:[1,0]
	v_pk_mul_f32 v[14:15], v[34:35], v[148:149] op_sel_hi:[1,0]
	v_pk_mul_f32 v[2:3], v[2:3], v[132:133] op_sel_hi:[1,0]
	v_cvt_pk_bf16_f32 v250, v14, v15
	v_cvt_pk_bf16_f32 v251, v6, v7
	s_nop 1
	v_permlane16_swap_b32_e32 v248, v250
	v_permlane16_swap_b32_e32 v249, v251
	v_lshl_add_u64 v[242:243], v[4:5], 0, v[176:177]
	global_store_dwordx4 v[242:243], v[248:251], off
	v_pk_mul_f32 v[6:7], v[28:29], v[130:131] op_sel_hi:[1,0]
	v_pk_mul_f32 v[14:15], v[26:27], v[130:131] op_sel_hi:[1,0]
	v_lshl_add_u64 v[4:5], v[66:67], 0, v[78:79]
	v_cvt_pk_bf16_f32 v180, v14, v15
	v_cvt_pk_bf16_f32 v181, v6, v7
	v_pk_mul_f32 v[6:7], v[20:21], v[130:131] op_sel_hi:[1,0]
	v_pk_mul_f32 v[14:15], v[18:19], v[130:131] op_sel_hi:[1,0]
	v_pk_mul_f32 v[0:1], v[0:1], v[132:133] op_sel_hi:[1,0]
	v_cvt_pk_bf16_f32 v182, v14, v15
	v_cvt_pk_bf16_f32 v183, v6, v7
	v_pk_mul_f32 v[6:7], v[10:11], v[132:133] op_sel_hi:[1,0]
	s_nop 1
	v_permlane16_swap_b32_e32 v180, v182
	v_permlane16_swap_b32_e32 v181, v183
	v_lshl_add_u64 v[172:173], v[4:5], 0, v[176:177]
	global_store_dwordx4 v[172:173], v[180:183], off
	v_lshl_add_u64 v[4:5], v[66:67], 0, v[80:81]
	v_cvt_pk_bf16_f32 v184, v8, v9
	v_cvt_pk_bf16_f32 v185, v6, v7
	v_cvt_pk_bf16_f32 v186, v0, v1
	v_cvt_pk_bf16_f32 v187, v2, v3
	s_mov_b64 s[6:7], -1
	s_andn2_b64 vcc, exec, s[4:5]
	global_store_dwordx2 v[68:69], v[62:63], off
	global_store_dwordx2 v[54:55], v[46:47], off
	global_store_dwordx2 v[38:39], v[30:31], off
	s_nop 1
	v_permlane16_swap_b32_e32 v184, v186
	v_permlane16_swap_b32_e32 v185, v187
	v_lshl_add_u64 v[174:175], v[4:5], 0, v[176:177]
	global_store_dwordx4 v[174:175], v[184:187], off
	s_cbranch_vccnz .LBB0_563
	s_andn2_b64 vcc, exec, s[8:9]
	s_cbranch_vccnz .LBB0_562
	s_barrier
	s_branch .LBB0_562
